# layer-0 activation cast loop: 8 rows per memory round trip (was one load + full wait per row), same arithmetic order
# speedup vs baseline: 1.0064x; 1.0064x over previous
; __device__ __forceinline__ unsigned cvt_pk(float lo, float hi) { f32x2_t v = {lo, hi}; bf16x2_t b = __builtin_convertvector(v, bf16x2_t); return __builtin_bit_cast(unsigned, b); }
; __device__ __forceinline__ int fresh_bid() { int t; asm volatile("s_mov_b32 %0, %1" : "=s"(t) : "s"(blockIdx.x)); return t; }
; __device__ __forceinline__ void phase_convert(const Ctx& a, int l, LAS unsigned char* lds) {
;     ...
;         for (int r2 = fresh_bid(); r2 < T / 2; r2 += gridDim.x) {
;             int row = r2 * 2 + (tid >> 8), tt = tid & 255;
;             f32x4 v = *(const f32x4*)(x + (size_t)row * DM + tt * 4);
;             u32x2 w; w[0] = cvt_pk(v[0], v[1]); w[1] = cvt_pk(v[2], v[3]);
;             *(u32x2*)(xb + (size_t)row * DM + tt * 4) = w;
;             float ss = wave_sum(v[0] * v[0] + v[1] * v[1] + v[2] * v[2] + v[3] * v[3]);
;             if ((tid & 63) == 0) ssq[(size_t)row * 4 + (tt >> 6)] = ss;
.Lxb_grp:
	s_mul_i32 s0, s9, 7
	s_add_i32 s0, s0, s12
	s_cmpk_gt_i32 s0, 0x1fff
	s_cbranch_scc1 .LBB0_799
	v_mov_b32_e32 v34, v8
	v_mov_b32_e32 v35, 0
	v_add_u32_e32 v36, s13, v34
	v_mov_b32_e32 v37, 0
	v_add_u32_e32 v38, s13, v36
	v_mov_b32_e32 v39, 0
	v_add_u32_e32 v40, s13, v38
	v_mov_b32_e32 v41, 0
	v_add_u32_e32 v42, s13, v40
	v_mov_b32_e32 v43, 0
	v_add_u32_e32 v44, s13, v42
	v_mov_b32_e32 v45, 0
	v_add_u32_e32 v46, s13, v44
	v_mov_b32_e32 v47, 0
	v_add_u32_e32 v48, s13, v46
	v_mov_b32_e32 v49, 0
	v_lshlrev_b64 v[50:51], 12, v[34:35]
	v_lshl_add_u64 v[50:51], v[2:3], 0, v[50:51]
	global_load_dwordx4 v[52:55], v[50:51], off
	v_lshlrev_b64 v[50:51], 12, v[36:37]
	v_lshl_add_u64 v[50:51], v[2:3], 0, v[50:51]
	global_load_dwordx4 v[56:59], v[50:51], off
	v_lshlrev_b64 v[50:51], 12, v[38:39]
	v_lshl_add_u64 v[50:51], v[2:3], 0, v[50:51]
	global_load_dwordx4 v[60:63], v[50:51], off
	v_lshlrev_b64 v[50:51], 12, v[40:41]
	v_lshl_add_u64 v[50:51], v[2:3], 0, v[50:51]
	global_load_dwordx4 v[64:67], v[50:51], off
	v_lshlrev_b64 v[50:51], 12, v[42:43]
	v_lshl_add_u64 v[50:51], v[2:3], 0, v[50:51]
	global_load_dwordx4 v[68:71], v[50:51], off
	v_lshlrev_b64 v[50:51], 12, v[44:45]
	v_lshl_add_u64 v[50:51], v[2:3], 0, v[50:51]
	global_load_dwordx4 v[72:75], v[50:51], off
	v_lshlrev_b64 v[50:51], 12, v[46:47]
	v_lshl_add_u64 v[50:51], v[2:3], 0, v[50:51]
	global_load_dwordx4 v[76:79], v[50:51], off
	v_lshlrev_b64 v[50:51], 12, v[48:49]
	v_lshl_add_u64 v[50:51], v[2:3], 0, v[50:51]
	global_load_dwordx4 v[80:83], v[50:51], off
	s_waitcnt vmcnt(0)
	v_mul_f32_e32 v84, v53, v53
	v_fmac_f32_e32 v84, v52, v52
	v_fmac_f32_e32 v84, v54, v54
	v_fmac_f32_e32 v84, v55, v55
	v_mul_f32_e32 v85, v57, v57
	v_fmac_f32_e32 v85, v56, v56
	v_fmac_f32_e32 v85, v58, v58
	v_fmac_f32_e32 v85, v59, v59
	v_mul_f32_e32 v86, v61, v61
	v_fmac_f32_e32 v86, v60, v60
	v_fmac_f32_e32 v86, v62, v62
	v_fmac_f32_e32 v86, v63, v63
	v_mul_f32_e32 v87, v65, v65
	v_fmac_f32_e32 v87, v64, v64
	v_fmac_f32_e32 v87, v66, v66
	v_fmac_f32_e32 v87, v67, v67
	v_mul_f32_e32 v88, v69, v69
	v_fmac_f32_e32 v88, v68, v68
	v_fmac_f32_e32 v88, v70, v70
	v_fmac_f32_e32 v88, v71, v71
	v_mul_f32_e32 v89, v73, v73
	v_fmac_f32_e32 v89, v72, v72
	v_fmac_f32_e32 v89, v74, v74
	v_fmac_f32_e32 v89, v75, v75
	v_mul_f32_e32 v90, v77, v77
	v_fmac_f32_e32 v90, v76, v76
	v_fmac_f32_e32 v90, v78, v78
	v_fmac_f32_e32 v90, v79, v79
	v_mul_f32_e32 v91, v81, v81
	v_fmac_f32_e32 v91, v80, v80
	v_fmac_f32_e32 v91, v82, v82
	v_fmac_f32_e32 v91, v83, v83
	ds_bpermute_b32 v92, v11, v84
	ds_bpermute_b32 v93, v11, v85
	ds_bpermute_b32 v94, v11, v86
	ds_bpermute_b32 v95, v11, v87
	ds_bpermute_b32 v96, v11, v88
	ds_bpermute_b32 v97, v11, v89
	ds_bpermute_b32 v98, v11, v90
	ds_bpermute_b32 v99, v11, v91
	v_cvt_pk_bf16_f32 v52, v52, v53
	v_cvt_pk_bf16_f32 v53, v54, v55
	v_lshlrev_b64 v[50:51], 11, v[34:35]
	v_lshl_add_u64 v[50:51], v[4:5], 0, v[50:51]
	global_store_dwordx2 v[50:51], v[52:53], off
	v_cvt_pk_bf16_f32 v56, v56, v57
	v_cvt_pk_bf16_f32 v57, v58, v59
	v_lshlrev_b64 v[50:51], 11, v[36:37]
	v_lshl_add_u64 v[50:51], v[4:5], 0, v[50:51]
	global_store_dwordx2 v[50:51], v[56:57], off
	v_cvt_pk_bf16_f32 v60, v60, v61
	v_cvt_pk_bf16_f32 v61, v62, v63
	v_lshlrev_b64 v[50:51], 11, v[38:39]
	v_lshl_add_u64 v[50:51], v[4:5], 0, v[50:51]
	global_store_dwordx2 v[50:51], v[60:61], off
	v_cvt_pk_bf16_f32 v64, v64, v65
	v_cvt_pk_bf16_f32 v65, v66, v67
	v_lshlrev_b64 v[50:51], 11, v[40:41]
	v_lshl_add_u64 v[50:51], v[4:5], 0, v[50:51]
	global_store_dwordx2 v[50:51], v[64:65], off
	v_cvt_pk_bf16_f32 v68, v68, v69
	v_cvt_pk_bf16_f32 v69, v70, v71
	v_lshlrev_b64 v[50:51], 11, v[42:43]
	v_lshl_add_u64 v[50:51], v[4:5], 0, v[50:51]
	global_store_dwordx2 v[50:51], v[68:69], off
	v_cvt_pk_bf16_f32 v72, v72, v73
	v_cvt_pk_bf16_f32 v73, v74, v75
	v_lshlrev_b64 v[50:51], 11, v[44:45]
	v_lshl_add_u64 v[50:51], v[4:5], 0, v[50:51]
	global_store_dwordx2 v[50:51], v[72:73], off
	v_cvt_pk_bf16_f32 v76, v76, v77
	v_cvt_pk_bf16_f32 v77, v78, v79
	v_lshlrev_b64 v[50:51], 11, v[46:47]
	v_lshl_add_u64 v[50:51], v[4:5], 0, v[50:51]
	global_store_dwordx2 v[50:51], v[76:77], off
	v_cvt_pk_bf16_f32 v80, v80, v81
	v_cvt_pk_bf16_f32 v81, v82, v83
	v_lshlrev_b64 v[50:51], 11, v[48:49]
	v_lshl_add_u64 v[50:51], v[4:5], 0, v[50:51]
	global_store_dwordx2 v[50:51], v[80:81], off
	s_waitcnt lgkmcnt(0)
; __device__ __forceinline__ void phase_convert(const Ctx& a, int l, LAS unsigned char* lds) {
;     ...
;             float ss = wave_sum(v[0] * v[0] + v[1] * v[1] + v[2] * v[2] + v[3] * v[3]);
;             if ((tid & 63) == 0) ssq[(size_t)row * 4 + (tt >> 6)] = ss;
;         }
	v_add_f32_e32 v84, v84, v92
	v_add_f32_e32 v85, v85, v93
	v_add_f32_e32 v86, v86, v94
	v_add_f32_e32 v87, v87, v95
	v_add_f32_e32 v88, v88, v96
	v_add_f32_e32 v89, v89, v97
	v_add_f32_e32 v90, v90, v98
	v_add_f32_e32 v91, v91, v99
	ds_bpermute_b32 v92, v12, v84
	ds_bpermute_b32 v93, v12, v85
	ds_bpermute_b32 v94, v12, v86
	ds_bpermute_b32 v95, v12, v87
	ds_bpermute_b32 v96, v12, v88
	ds_bpermute_b32 v97, v12, v89
	ds_bpermute_b32 v98, v12, v90
	ds_bpermute_b32 v99, v12, v91
	s_waitcnt lgkmcnt(0)
	v_add_f32_e32 v84, v84, v92
	v_add_f32_e32 v85, v85, v93
	v_add_f32_e32 v86, v86, v94
	v_add_f32_e32 v87, v87, v95
	v_add_f32_e32 v88, v88, v96
	v_add_f32_e32 v89, v89, v97
	v_add_f32_e32 v90, v90, v98
	v_add_f32_e32 v91, v91, v99
	ds_bpermute_b32 v92, v13, v84
	ds_bpermute_b32 v93, v13, v85
	ds_bpermute_b32 v94, v13, v86
	ds_bpermute_b32 v95, v13, v87
	ds_bpermute_b32 v96, v13, v88
	ds_bpermute_b32 v97, v13, v89
	ds_bpermute_b32 v98, v13, v90
	ds_bpermute_b32 v99, v13, v91
	s_waitcnt lgkmcnt(0)
	v_add_f32_e32 v84, v84, v92
	v_add_f32_e32 v85, v85, v93
	v_add_f32_e32 v86, v86, v94
	v_add_f32_e32 v87, v87, v95
	v_add_f32_e32 v88, v88, v96
	v_add_f32_e32 v89, v89, v97
	v_add_f32_e32 v90, v90, v98
	v_add_f32_e32 v91, v91, v99
	ds_bpermute_b32 v92, v14, v84
	ds_bpermute_b32 v93, v14, v85
	ds_bpermute_b32 v94, v14, v86
	ds_bpermute_b32 v95, v14, v87
	ds_bpermute_b32 v96, v14, v88
	ds_bpermute_b32 v97, v14, v89
	ds_bpermute_b32 v98, v14, v90
	ds_bpermute_b32 v99, v14, v91
	s_waitcnt lgkmcnt(0)
	v_add_f32_e32 v84, v84, v92
	v_add_f32_e32 v85, v85, v93
	v_add_f32_e32 v86, v86, v94
	v_add_f32_e32 v87, v87, v95
	v_add_f32_e32 v88, v88, v96
	v_add_f32_e32 v89, v89, v97
	v_add_f32_e32 v90, v90, v98
	v_add_f32_e32 v91, v91, v99
	ds_bpermute_b32 v92, v15, v84
	ds_bpermute_b32 v93, v15, v85
	ds_bpermute_b32 v94, v15, v86
	ds_bpermute_b32 v95, v15, v87
	ds_bpermute_b32 v96, v15, v88
	ds_bpermute_b32 v97, v15, v89
	ds_bpermute_b32 v98, v15, v90
	ds_bpermute_b32 v99, v15, v91
	s_waitcnt lgkmcnt(0)
	v_add_f32_e32 v84, v84, v92
	v_add_f32_e32 v85, v85, v93
	v_add_f32_e32 v86, v86, v94
	v_add_f32_e32 v87, v87, v95
	v_add_f32_e32 v88, v88, v96
	v_add_f32_e32 v89, v89, v97
	v_add_f32_e32 v90, v90, v98
	v_add_f32_e32 v91, v91, v99
	ds_bpermute_b32 v92, v16, v84
	ds_bpermute_b32 v93, v16, v85
	ds_bpermute_b32 v94, v16, v86
	ds_bpermute_b32 v95, v16, v87
	ds_bpermute_b32 v96, v16, v88
	ds_bpermute_b32 v97, v16, v89
	ds_bpermute_b32 v98, v16, v90
	ds_bpermute_b32 v99, v16, v91
	s_waitcnt lgkmcnt(0)
	v_add_f32_e32 v84, v84, v92
	v_add_f32_e32 v85, v85, v93
	v_add_f32_e32 v86, v86, v94
	v_add_f32_e32 v87, v87, v95
	v_add_f32_e32 v88, v88, v96
	v_add_f32_e32 v89, v89, v97
	v_add_f32_e32 v90, v90, v98
	v_add_f32_e32 v91, v91, v99
	s_and_saveexec_b64 s[0:1], vcc
	v_lshl_add_u64 v[50:51], v[34:35], 4, v[6:7]
	global_store_dword v[50:51], v84, off
	v_lshl_add_u64 v[50:51], v[36:37], 4, v[6:7]
	global_store_dword v[50:51], v85, off
	v_lshl_add_u64 v[50:51], v[38:39], 4, v[6:7]
	global_store_dword v[50:51], v86, off
	v_lshl_add_u64 v[50:51], v[40:41], 4, v[6:7]
	global_store_dword v[50:51], v87, off
	v_lshl_add_u64 v[50:51], v[42:43], 4, v[6:7]
	global_store_dword v[50:51], v88, off
	v_lshl_add_u64 v[50:51], v[44:45], 4, v[6:7]
	global_store_dword v[50:51], v89, off
	v_lshl_add_u64 v[50:51], v[46:47], 4, v[6:7]
	global_store_dword v[50:51], v90, off
	v_lshl_add_u64 v[50:51], v[48:49], 4, v[6:7]
	global_store_dword v[50:51], v91, off
	s_or_b64 exec, exec, s[0:1]
	s_lshl_b32 s0, s9, 3
	s_add_i32 s12, s12, s0
	s_lshl_b32 s0, s13, 3
	v_add_u32_e32 v8, s0, v8
	s_cmpk_gt_i32 s12, 0x1fff
	s_cbranch_scc1 .LBB0_801
	s_branch .Lxb_grp
